# P3 epilogue x loads software-pipelined 8 units ahead; mid-K row statistics prefetched at tile start (8B per lane + permlane reduce)
# baseline (speedup 1.0000x reference)
;     __device__ __forceinline__ void mid(f32x4 (&acc)[2][2][4][2], const Unit& u, int wr, int wc, int fr, int fq) const {
;     ...
;                 const size_t row = (size_t)u.pm * 256 + 128 * wr + 64 * ai + 16 * m + fr;
;                 const f32x4* sp = (const f32x4*)(ssqA + row * 8);
;                 const f32x4 t = sp[0] + sp[1];
; template <class Epi, class Sched>
; __device__ __forceinline__ void gemm_phase(LAS unsigned char* lds, const Gemm g, const Sched& S, const Epi& E) {
;     ...
;         for (int a = 0; a < 2; ++a)
; #pragma unroll
;             for (int b = 0; b < 2; ++b)
; #pragma unroll
;                 for (int m = 0; m < 4; ++m)
; #pragma unroll
;                     for (int n = 0; n < 2; ++n) acc[a][b][m][n] = (f32x4){0.f, 0.f, 0.f, 0.f};
;         cur = nxt; cA = nA; cB = nB; ++ui;
.LBB0_615:
	s_ashr_i32 s13, s12, 31
	s_lshl_b64 s[16:17], s[12:13], 19
	v_readlane_b32 s18, v243, 20
	v_readlane_b32 s19, v243, 21
	s_add_u32 s16, s18, s16
	s_addc_u32 s17, s19, s17
	s_and_b64 s[18:19], s[6:7], exec
	s_cselect_b32 s13, s17, s25
	s_cselect_b32 s62, s16, s24
	s_ashr_i32 s15, s14, 31
	s_lshl_b64 s[18:19], s[14:15], 19
	s_add_u32 s18, s94, s18
	s_addc_u32 s19, s95, s19
	s_and_b64 s[30:31], s[6:7], exec
	s_cselect_b32 s15, s19, s29
	s_cselect_b32 s63, s18, s28
	s_ashr_i32 s27, s26, 31
	s_lshl_b64 s[26:27], s[26:27], 8
	v_lshl_add_u64 v[168:169], s[26:27], 0, v[158:159]
	v_lshl_add_u64 v[6:7], v[160:161], 0, s[26:27]
	v_lshlrev_b64 v[4:5], 5, v[168:169]
	v_lshlrev_b64 v[6:7], 5, v[6:7]
	v_or_b32_e32 v8, 0x200, v6
	v_mov_b32_e32 v9, v7
	v_or_b32_e32 v10, 0x400, v6
	v_mov_b32_e32 v11, v7
	v_or_b32_e32 v12, 0x600, v6
	v_mov_b32_e32 v13, v7
	v_lshl_add_u64 v[170:171], s[34:35], 0, v[4:5]
	v_mov_b32_e32 v4, v2
	v_mov_b32_e32 v5, v2
	v_lshl_add_u64 v[172:173], s[34:35], 0, v[6:7]
	v_lshl_add_u64 v[174:175], s[34:35], 0, v[8:9]
	v_lshl_add_u64 v[176:177], s[34:35], 0, v[10:11]
	v_lshl_add_u64 v[178:179], s[34:35], 0, v[12:13]
	v_bfe_u32 v252, v0, 4, 2
	v_lshlrev_b32_e32 v252, 3, v252
	v_mov_b32_e32 v253, 0
	v_lshl_add_u64 v[254:255], v[172:173], 0, v[252:253]
	v_lshl_add_u64 v[252:253], v[170:171], 0, v[252:253]
	global_load_dwordx2 v[226:227], v[252:253], off
	global_load_dwordx2 v[228:229], v[252:253], off offset:512
	global_load_dwordx2 v[230:231], v[252:253], off offset:1024
	global_load_dwordx2 v[232:233], v[252:253], off offset:1536
	global_load_dwordx2 v[234:235], v[254:255], off
	global_load_dwordx2 v[236:237], v[254:255], off offset:512
	global_load_dwordx2 v[238:239], v[254:255], off offset:1024
	global_load_dwordx2 v[240:241], v[254:255], off offset:1536
	s_add_u32 s64, s28, 0x100
	v_mov_b32_e32 v3, v2
	v_mov_b64_e32 v[8:9], v[4:5]
	v_mov_b64_e32 v[12:13], v[4:5]
	v_mov_b64_e32 v[24:25], v[4:5]
	v_mov_b64_e32 v[28:29], v[4:5]
	v_mov_b64_e32 v[40:41], v[4:5]
	v_mov_b64_e32 v[44:45], v[4:5]
	v_mov_b64_e32 v[56:57], v[4:5]
	v_mov_b64_e32 v[60:61], v[4:5]
	v_mov_b64_e32 v[16:17], v[4:5]
	v_mov_b64_e32 v[20:21], v[4:5]
	v_mov_b64_e32 v[32:33], v[4:5]
	v_mov_b64_e32 v[36:37], v[4:5]
	v_mov_b64_e32 v[48:49], v[4:5]
	v_mov_b64_e32 v[52:53], v[4:5]
	v_mov_b64_e32 v[64:65], v[4:5]
	v_mov_b64_e32 v[68:69], v[4:5]
	v_mov_b64_e32 v[72:73], v[4:5]
	v_mov_b64_e32 v[76:77], v[4:5]
	v_mov_b64_e32 v[88:89], v[4:5]
	v_mov_b64_e32 v[92:93], v[4:5]
	v_mov_b64_e32 v[104:105], v[4:5]
	v_mov_b64_e32 v[108:109], v[4:5]
	v_mov_b64_e32 v[120:121], v[4:5]
	v_mov_b64_e32 v[124:125], v[4:5]
	v_mov_b64_e32 v[80:81], v[4:5]
	v_mov_b64_e32 v[84:85], v[4:5]
	v_mov_b64_e32 v[96:97], v[4:5]
	v_mov_b64_e32 v[100:101], v[4:5]
	v_mov_b64_e32 v[112:113], v[4:5]
	v_mov_b64_e32 v[116:117], v[4:5]
	v_mov_b64_e32 v[128:129], v[4:5]
	v_mov_b64_e32 v[132:133], v[4:5]
	s_addc_u32 s65, s29, 0
	s_mov_b32 s66, -2
	v_mov_b64_e32 v[6:7], v[2:3]
	v_mov_b64_e32 v[10:11], v[2:3]
	v_mov_b64_e32 v[22:23], v[2:3]
	v_mov_b64_e32 v[26:27], v[2:3]
	v_mov_b64_e32 v[38:39], v[2:3]
	v_mov_b64_e32 v[42:43], v[2:3]
	v_mov_b64_e32 v[54:55], v[2:3]
	v_mov_b64_e32 v[58:59], v[2:3]
	v_mov_b64_e32 v[14:15], v[2:3]
	v_mov_b64_e32 v[18:19], v[2:3]
	v_mov_b64_e32 v[30:31], v[2:3]
	v_mov_b64_e32 v[34:35], v[2:3]
	v_mov_b64_e32 v[46:47], v[2:3]
	v_mov_b64_e32 v[50:51], v[2:3]
	v_mov_b64_e32 v[62:63], v[2:3]
	v_mov_b64_e32 v[66:67], v[2:3]
	v_mov_b64_e32 v[70:71], v[2:3]
	v_mov_b64_e32 v[74:75], v[2:3]
	v_mov_b64_e32 v[86:87], v[2:3]
	v_mov_b64_e32 v[90:91], v[2:3]
	v_mov_b64_e32 v[102:103], v[2:3]
	v_mov_b64_e32 v[106:107], v[2:3]
	v_mov_b64_e32 v[118:119], v[2:3]
	v_mov_b64_e32 v[122:123], v[2:3]
	v_mov_b64_e32 v[78:79], v[2:3]
	v_mov_b64_e32 v[82:83], v[2:3]
	v_mov_b64_e32 v[94:95], v[2:3]
	v_mov_b64_e32 v[98:99], v[2:3]
	v_mov_b64_e32 v[110:111], v[2:3]
	v_mov_b64_e32 v[114:115], v[2:3]
	v_mov_b64_e32 v[126:127], v[2:3]
	v_mov_b64_e32 v[130:131], v[2:3]
	s_cmp_lg_u32 s66, 6
	s_cbranch_scc1 .LBB0_618
	s_branch .LBB0_617

;     __device__ __forceinline__ void mid(f32x4 (&acc)[2][2][4][2], const Unit& u, int wr, int wc, int fr, int fq) const {
; #pragma unroll
;         for (int ai = 0; ai < 2; ++ai)
; #pragma unroll
;             for (int m = 0; m < 4; ++m) {
;                 const size_t row = (size_t)u.pm * 256 + 128 * wr + 64 * ai + 16 * m + fr;
;                 const f32x4* sp = (const f32x4*)(ssqA + row * 8);
;                 const f32x4 t = sp[0] + sp[1];
;                 const float r = __builtin_amdgcn_rsqf(((t[0] + t[1]) + (t[2] + t[3])) * (1.0f / AW) + EPS);
; #pragma unroll
;                 for (int bj = 0; bj < 2; ++bj)
; #pragma unroll
;                     for (int n = 0; n < 2; ++n) acc[ai][bj][m][n] = acc[ai][bj][m][n] * r;
;             }
;     }
.LBB0_617:
	s_waitcnt vmcnt(8)
	v_add_f32_e32 v226, v226, v227
	v_add_f32_e32 v228, v228, v229
	v_add_f32_e32 v230, v230, v231
	v_add_f32_e32 v232, v232, v233
	v_add_f32_e32 v234, v234, v235
	v_add_f32_e32 v236, v236, v237
	v_add_f32_e32 v238, v238, v239
	v_add_f32_e32 v240, v240, v241
	v_mov_b32_e32 v227, v226
	v_mov_b32_e32 v229, v228
	v_mov_b32_e32 v231, v230
	v_mov_b32_e32 v233, v232
	v_mov_b32_e32 v235, v234
	v_mov_b32_e32 v237, v236
	v_mov_b32_e32 v239, v238
	v_mov_b32_e32 v241, v240
	v_permlane16_swap_b32_e32 v226, v227
	v_permlane16_swap_b32_e32 v228, v229
	v_permlane16_swap_b32_e32 v230, v231
	v_permlane16_swap_b32_e32 v232, v233
	v_permlane16_swap_b32_e32 v234, v235
	v_permlane16_swap_b32_e32 v236, v237
	v_permlane16_swap_b32_e32 v238, v239
	v_permlane16_swap_b32_e32 v240, v241
	v_add_f32_e32 v226, v226, v227
	v_add_f32_e32 v228, v228, v229
	v_add_f32_e32 v230, v230, v231
	v_add_f32_e32 v232, v232, v233
	v_add_f32_e32 v234, v234, v235
	v_add_f32_e32 v236, v236, v237
	v_add_f32_e32 v238, v238, v239
	v_add_f32_e32 v240, v240, v241
	v_mov_b32_e32 v227, v226
	v_mov_b32_e32 v229, v228
	v_mov_b32_e32 v231, v230
	v_mov_b32_e32 v233, v232
	v_mov_b32_e32 v235, v234
	v_mov_b32_e32 v237, v236
	v_mov_b32_e32 v239, v238
	v_mov_b32_e32 v241, v240
	v_permlane32_swap_b32_e32 v226, v227
	v_permlane32_swap_b32_e32 v228, v229
	v_permlane32_swap_b32_e32 v230, v231
	v_permlane32_swap_b32_e32 v232, v233
	v_permlane32_swap_b32_e32 v234, v235
	v_permlane32_swap_b32_e32 v236, v237
	v_permlane32_swap_b32_e32 v238, v239
	v_permlane32_swap_b32_e32 v240, v241
	v_add_f32_e32 v226, v226, v227
	v_add_f32_e32 v228, v228, v229
	v_add_f32_e32 v230, v230, v231
	v_add_f32_e32 v232, v232, v233
	v_add_f32_e32 v234, v234, v235
	v_add_f32_e32 v236, v236, v237
	v_add_f32_e32 v238, v238, v239
	v_add_f32_e32 v240, v240, v241
	v_fmamk_f32 v226, v226, 0x3b000000, v182
	v_fmamk_f32 v228, v228, 0x3b000000, v182
	v_fmamk_f32 v230, v230, 0x3b000000, v182
	v_fmamk_f32 v232, v232, 0x3b000000, v182
	v_fmamk_f32 v234, v234, 0x3b000000, v182
	v_fmamk_f32 v236, v236, 0x3b000000, v182
	v_fmamk_f32 v238, v238, 0x3b000000, v182
	v_fmamk_f32 v240, v240, 0x3b000000, v182
	v_rsq_f32_e32 v226, v226
	v_rsq_f32_e32 v228, v228
	v_rsq_f32_e32 v230, v230
	v_rsq_f32_e32 v232, v232
	v_rsq_f32_e32 v234, v234
	v_rsq_f32_e32 v236, v236
	v_rsq_f32_e32 v238, v238
	v_rsq_f32_e32 v240, v240
	v_pk_mul_f32 v[118:119], v[118:119], v[226:227] op_sel_hi:[1,0]
	v_pk_mul_f32 v[120:121], v[120:121], v[226:227] op_sel_hi:[1,0]
	v_pk_mul_f32 v[122:123], v[122:123], v[226:227] op_sel_hi:[1,0]
	v_pk_mul_f32 v[124:125], v[124:125], v[226:227] op_sel_hi:[1,0]
	v_pk_mul_f32 v[126:127], v[126:127], v[226:227] op_sel_hi:[1,0]
	v_pk_mul_f32 v[128:129], v[128:129], v[226:227] op_sel_hi:[1,0]
	v_pk_mul_f32 v[130:131], v[130:131], v[226:227] op_sel_hi:[1,0]
	v_pk_mul_f32 v[132:133], v[132:133], v[226:227] op_sel_hi:[1,0]
	v_pk_mul_f32 v[102:103], v[102:103], v[228:229] op_sel_hi:[1,0]
	v_pk_mul_f32 v[104:105], v[104:105], v[228:229] op_sel_hi:[1,0]
	v_pk_mul_f32 v[106:107], v[106:107], v[228:229] op_sel_hi:[1,0]
	v_pk_mul_f32 v[108:109], v[108:109], v[228:229] op_sel_hi:[1,0]
	v_pk_mul_f32 v[110:111], v[110:111], v[228:229] op_sel_hi:[1,0]
	v_pk_mul_f32 v[112:113], v[112:113], v[228:229] op_sel_hi:[1,0]
	v_pk_mul_f32 v[114:115], v[114:115], v[228:229] op_sel_hi:[1,0]
	v_pk_mul_f32 v[116:117], v[116:117], v[228:229] op_sel_hi:[1,0]
	v_pk_mul_f32 v[86:87], v[86:87], v[230:231] op_sel_hi:[1,0]
	v_pk_mul_f32 v[88:89], v[88:89], v[230:231] op_sel_hi:[1,0]
	v_pk_mul_f32 v[90:91], v[90:91], v[230:231] op_sel_hi:[1,0]
	v_pk_mul_f32 v[92:93], v[92:93], v[230:231] op_sel_hi:[1,0]
	v_pk_mul_f32 v[94:95], v[94:95], v[230:231] op_sel_hi:[1,0]
	v_pk_mul_f32 v[96:97], v[96:97], v[230:231] op_sel_hi:[1,0]
	v_pk_mul_f32 v[98:99], v[98:99], v[230:231] op_sel_hi:[1,0]
	v_pk_mul_f32 v[100:101], v[100:101], v[230:231] op_sel_hi:[1,0]
	v_pk_mul_f32 v[70:71], v[70:71], v[232:233] op_sel_hi:[1,0]
	v_pk_mul_f32 v[72:73], v[72:73], v[232:233] op_sel_hi:[1,0]
	v_pk_mul_f32 v[74:75], v[74:75], v[232:233] op_sel_hi:[1,0]
	v_pk_mul_f32 v[76:77], v[76:77], v[232:233] op_sel_hi:[1,0]
	v_pk_mul_f32 v[78:79], v[78:79], v[232:233] op_sel_hi:[1,0]
	v_pk_mul_f32 v[80:81], v[80:81], v[232:233] op_sel_hi:[1,0]
	v_pk_mul_f32 v[82:83], v[82:83], v[232:233] op_sel_hi:[1,0]
	v_pk_mul_f32 v[84:85], v[84:85], v[232:233] op_sel_hi:[1,0]
	v_pk_mul_f32 v[54:55], v[54:55], v[234:235] op_sel_hi:[1,0]
	v_pk_mul_f32 v[56:57], v[56:57], v[234:235] op_sel_hi:[1,0]
	v_pk_mul_f32 v[58:59], v[58:59], v[234:235] op_sel_hi:[1,0]
	v_pk_mul_f32 v[60:61], v[60:61], v[234:235] op_sel_hi:[1,0]
	v_pk_mul_f32 v[62:63], v[62:63], v[234:235] op_sel_hi:[1,0]
	v_pk_mul_f32 v[64:65], v[64:65], v[234:235] op_sel_hi:[1,0]
	v_pk_mul_f32 v[66:67], v[66:67], v[234:235] op_sel_hi:[1,0]
	v_pk_mul_f32 v[68:69], v[68:69], v[234:235] op_sel_hi:[1,0]
	v_pk_mul_f32 v[38:39], v[38:39], v[236:237] op_sel_hi:[1,0]
	v_pk_mul_f32 v[40:41], v[40:41], v[236:237] op_sel_hi:[1,0]
	v_pk_mul_f32 v[42:43], v[42:43], v[236:237] op_sel_hi:[1,0]
	v_pk_mul_f32 v[44:45], v[44:45], v[236:237] op_sel_hi:[1,0]
	v_pk_mul_f32 v[46:47], v[46:47], v[236:237] op_sel_hi:[1,0]
	v_pk_mul_f32 v[48:49], v[48:49], v[236:237] op_sel_hi:[1,0]
	v_pk_mul_f32 v[50:51], v[50:51], v[236:237] op_sel_hi:[1,0]
	v_pk_mul_f32 v[52:53], v[52:53], v[236:237] op_sel_hi:[1,0]
	v_pk_mul_f32 v[22:23], v[22:23], v[238:239] op_sel_hi:[1,0]
	v_pk_mul_f32 v[24:25], v[24:25], v[238:239] op_sel_hi:[1,0]
	v_pk_mul_f32 v[26:27], v[26:27], v[238:239] op_sel_hi:[1,0]
	v_pk_mul_f32 v[28:29], v[28:29], v[238:239] op_sel_hi:[1,0]
	v_pk_mul_f32 v[30:31], v[30:31], v[238:239] op_sel_hi:[1,0]
	v_pk_mul_f32 v[32:33], v[32:33], v[238:239] op_sel_hi:[1,0]
	v_pk_mul_f32 v[34:35], v[34:35], v[238:239] op_sel_hi:[1,0]
	v_pk_mul_f32 v[36:37], v[36:37], v[238:239] op_sel_hi:[1,0]
	v_pk_mul_f32 v[6:7], v[6:7], v[240:241] op_sel_hi:[1,0]
	v_pk_mul_f32 v[8:9], v[8:9], v[240:241] op_sel_hi:[1,0]
	v_pk_mul_f32 v[10:11], v[10:11], v[240:241] op_sel_hi:[1,0]
	v_pk_mul_f32 v[12:13], v[12:13], v[240:241] op_sel_hi:[1,0]
	v_pk_mul_f32 v[14:15], v[14:15], v[240:241] op_sel_hi:[1,0]
	v_pk_mul_f32 v[16:17], v[16:17], v[240:241] op_sel_hi:[1,0]
	v_pk_mul_f32 v[18:19], v[18:19], v[240:241] op_sel_hi:[1,0]
	v_pk_mul_f32 v[20:21], v[20:21], v[240:241] op_sel_hi:[1,0]

; __device__ __forceinline__ unsigned pk2(float lo, float hi) { f32x2 v = {lo, hi}; bf16x2_t b = __builtin_convertvector(v, bf16x2_t); return __builtin_bit_cast(unsigned, b); }
;     __device__ __forceinline__ void operator()(const f32x4 (&acc)[2][2][4][2], const Unit& u, int wr, int wc, int fr, int fq) const {
; #pragma unroll
;         for (int ai = 0; ai < 2; ++ai)
; #pragma unroll
;             for (int m = 0; m < 4; ++m) {
;                 const size_t row = (size_t)u.pm * 256 + 128 * wr + 64 * ai + 16 * m + fr;
;                 const size_t off = row * DM + 256 * u.pn + 32 * wc + 8 * fq;
;                 float s = 0.f;
; #pragma unroll
;                 for (int bj = 0; bj < 2; ++bj) {
;                     const f32x4 v0 = *(const f32x4*)(x + off + 128 * bj) + acc[ai][bj][m][0], v1 = *(const f32x4*)(x + off + 128 * bj + 4) + acc[ai][bj][m][1];
;                     s += (v0[0] * v0[0] + v0[1] * v0[1]) + (v0[2] * v0[2] + v0[3] * v0[3]) + (v1[0] * v1[0] + v1[1] * v1[1]) + (v1[2] * v1[2] + v1[3] * v1[3]);
;                     u32x4 w; w.x = pk2(v0[0], v0[1]); w.y = pk2(v0[2], v0[3]); w.z = pk2(v1[0], v1[1]); w.w = pk2(v1[2], v1[3]);
;                     *(u32x4*)(XB + off + 128 * bj) = w;
;                 }
;                 s = xor16_32_sum(s);
;                 if (fq == 0) ssq[row * 16 + u.pn * 4 + wc] = s;
;             }
.LBB0_621:
	s_lshl_b32 s13, s0, 8
	s_ashr_i32 s15, s13, 31
	v_mov_b32_e32 v5, s15
	v_or_b32_e32 v4, s13, v162
	v_lshlrev_b64 v[150:151], 10, v[168:169]
	v_readlane_b32 s68, v243, 4
	v_readlane_b32 s69, v243, 5
	v_lshl_add_u64 v[150:151], v[150:151], 0, v[4:5]
	s_lshl_b32 s24, s0, 2
	s_ashr_i32 s25, s24, 31
	v_lshl_add_u64 v[142:143], v[150:151], 2, s[68:69]
	v_lshl_add_u64 v[144:145], v[150:151], 1, s[42:43]
	s_mov_b64 s[62:63], 0x10000
	s_mov_b64 s[64:65], 0x8000
	s_mov_b64 s[28:29], 0x400
	global_load_dwordx4 v[186:189], v[142:143], off
	global_load_dwordx4 v[190:193], v[142:143], off offset:16
	global_load_dwordx4 v[194:197], v[142:143], off offset:512
	global_load_dwordx4 v[198:201], v[142:143], off offset:528
	v_lshl_add_u64 v[142:143], v[142:143], 0, s[62:63]
	global_load_dwordx4 v[202:205], v[142:143], off
	global_load_dwordx4 v[206:209], v[142:143], off offset:16
	global_load_dwordx4 v[210:213], v[142:143], off offset:512
	global_load_dwordx4 v[214:217], v[142:143], off offset:528
	v_lshl_add_u64 v[142:143], v[142:143], 0, s[62:63]
	global_load_dwordx4 v[218:221], v[142:143], off
	global_load_dwordx4 v[222:225], v[142:143], off offset:16
	global_load_dwordx4 v[226:229], v[142:143], off offset:512
	global_load_dwordx4 v[230:233], v[142:143], off offset:528
	v_lshl_add_u64 v[142:143], v[142:143], 0, s[62:63]
	global_load_dwordx4 v[234:237], v[142:143], off
	global_load_dwordx4 v[238:241], v[142:143], off offset:16
	global_load_dwordx4 v[134:137], v[142:143], off offset:512
	global_load_dwordx4 v[138:141], v[142:143], off offset:528
	v_lshl_add_u64 v[142:143], v[142:143], 0, s[62:63]
	v_lshlrev_b64 v[146:147], 6, v[168:169]
	v_lshl_add_u64 v[146:147], s[40:41], 0, v[146:147]
	v_lshl_add_u64 v[146:147], s[24:25], 2, v[146:147]
	s_lshl_b32 s0, s50, 2
	v_lshl_add_u64 v[146:147], v[146:147], 0, s[0:1]
	s_waitcnt vmcnt(14)
	v_pk_add_f32 v[188:189], v[132:133], v[188:189]
	v_pk_add_f32 v[186:187], v[130:131], v[186:187]
	v_pk_add_f32 v[192:193], v[128:129], v[192:193]
	v_pk_add_f32 v[190:191], v[126:127], v[190:191]
	v_cvt_pk_bf16_f32 v130, v186, v187
	v_cvt_pk_bf16_f32 v131, v188, v189
	v_cvt_pk_bf16_f32 v132, v190, v191
	v_cvt_pk_bf16_f32 v133, v192, v193
	global_store_dwordx4 v[144:145], v[130:133], off
	v_mul_f32_e32 v3, v187, v187
	v_mul_f32_e32 v189, v189, v189
	v_mul_f32_e32 v191, v191, v191
	v_fmac_f32_e32 v3, v186, v186
	v_fmac_f32_e32 v189, v188, v188
	v_mul_f32_e32 v193, v193, v193
	v_fmac_f32_e32 v191, v190, v190
	v_add_f32_e32 v3, v3, v189
	v_fmac_f32_e32 v193, v192, v192
	v_add_f32_e32 v3, v3, v191
	v_add_f32_e32 v3, v193, v3
	global_load_dwordx4 v[186:189], v[142:143], off
	global_load_dwordx4 v[190:193], v[142:143], off offset:16
	s_waitcnt vmcnt(15)
	v_pk_add_f32 v[196:197], v[124:125], v[196:197]
	v_pk_add_f32 v[194:195], v[122:123], v[194:195]
	v_pk_add_f32 v[200:201], v[120:121], v[200:201]
	v_pk_add_f32 v[198:199], v[118:119], v[198:199]
	v_cvt_pk_bf16_f32 v122, v194, v195
	v_cvt_pk_bf16_f32 v123, v196, v197
	v_cvt_pk_bf16_f32 v124, v198, v199
	v_cvt_pk_bf16_f32 v125, v200, v201
	global_store_dwordx4 v[144:145], v[122:125], off offset:256
	v_mul_f32_e32 v195, v195, v195
	v_mul_f32_e32 v197, v197, v197
	v_mul_f32_e32 v199, v199, v199
	v_fmac_f32_e32 v195, v194, v194
	v_fmac_f32_e32 v197, v196, v196
	v_mul_f32_e32 v201, v201, v201
	v_fmac_f32_e32 v199, v198, v198
	v_fmac_f32_e32 v201, v200, v200
	v_add_f32_e32 v149, v195, v197
	v_add_f32_e32 v149, v149, v199
	v_add_f32_e32 v149, v201, v149
	v_add_f32_e32 v3, v3, v149
	global_load_dwordx4 v[194:197], v[142:143], off offset:512
	global_load_dwordx4 v[198:201], v[142:143], off offset:528
	v_lshl_add_u64 v[142:143], v[142:143], 0, s[62:63]
	v_mov_b32_e32 v148, v3
	v_lshl_add_u64 v[144:145], v[144:145], 0, s[64:65]
	s_nop 0
	v_permlane16_swap_b32_e32 v3, v148
	v_add_f32_e32 v3, v3, v148
	v_mov_b32_e32 v148, v3
	s_nop 1
	v_permlane32_swap_b32_e32 v3, v148
	v_add_f32_e32 v3, v3, v148
	s_and_saveexec_b64 s[26:27], s[4:5]
	global_store_dword v[146:147], v3, off
	s_or_b64 exec, exec, s[26:27]
	v_lshl_add_u64 v[146:147], v[146:147], 0, s[28:29]
	s_waitcnt vmcnt(16)
	v_pk_add_f32 v[204:205], v[116:117], v[204:205]
	v_pk_add_f32 v[202:203], v[114:115], v[202:203]
	v_pk_add_f32 v[208:209], v[112:113], v[208:209]
	v_pk_add_f32 v[206:207], v[110:111], v[206:207]
	v_cvt_pk_bf16_f32 v114, v202, v203
	v_cvt_pk_bf16_f32 v115, v204, v205
	v_cvt_pk_bf16_f32 v116, v206, v207
	v_cvt_pk_bf16_f32 v117, v208, v209
	global_store_dwordx4 v[144:145], v[114:117], off
	v_mul_f32_e32 v3, v203, v203
	v_mul_f32_e32 v205, v205, v205
	v_mul_f32_e32 v207, v207, v207
	v_fmac_f32_e32 v3, v202, v202
	v_fmac_f32_e32 v205, v204, v204
	v_mul_f32_e32 v209, v209, v209
	v_fmac_f32_e32 v207, v206, v206
	v_add_f32_e32 v3, v3, v205
	v_fmac_f32_e32 v209, v208, v208
	v_add_f32_e32 v3, v3, v207
	v_add_f32_e32 v3, v209, v3
	global_load_dwordx4 v[202:205], v[142:143], off
	global_load_dwordx4 v[206:209], v[142:143], off offset:16
	s_waitcnt vmcnt(17)
; __device__ __forceinline__ unsigned pk2(float lo, float hi) { f32x2 v = {lo, hi}; bf16x2_t b = __builtin_convertvector(v, bf16x2_t); return __builtin_bit_cast(unsigned, b); }
;     __device__ __forceinline__ void operator()(const f32x4 (&acc)[2][2][4][2], const Unit& u, int wr, int wc, int fr, int fq) const {
; #pragma unroll
;         for (int ai = 0; ai < 2; ++ai)
; #pragma unroll
;             for (int m = 0; m < 4; ++m) {
;                 const size_t row = (size_t)u.pm * 256 + 128 * wr + 64 * ai + 16 * m + fr;
;                 const size_t off = row * DM + 256 * u.pn + 32 * wc + 8 * fq;
;                 float s = 0.f;
; #pragma unroll
;                 for (int bj = 0; bj < 2; ++bj) {
;                     const f32x4 v0 = *(const f32x4*)(x + off + 128 * bj) + acc[ai][bj][m][0], v1 = *(const f32x4*)(x + off + 128 * bj + 4) + acc[ai][bj][m][1];
;                     s += (v0[0] * v0[0] + v0[1] * v0[1]) + (v0[2] * v0[2] + v0[3] * v0[3]) + (v1[0] * v1[0] + v1[1] * v1[1]) + (v1[2] * v1[2] + v1[3] * v1[3]);
;                     u32x4 w; w.x = pk2(v0[0], v0[1]); w.y = pk2(v0[2], v0[3]); w.z = pk2(v1[0], v1[1]); w.w = pk2(v1[2], v1[3]);
;                     *(u32x4*)(XB + off + 128 * bj) = w;
;                 }
;                 s = xor16_32_sum(s);
;                 if (fq == 0) ssq[row * 16 + u.pn * 4 + wc] = s;
;             }
	v_pk_add_f32 v[212:213], v[108:109], v[212:213]
	v_pk_add_f32 v[210:211], v[106:107], v[210:211]
	v_pk_add_f32 v[216:217], v[104:105], v[216:217]
	v_pk_add_f32 v[214:215], v[102:103], v[214:215]
	v_cvt_pk_bf16_f32 v106, v210, v211
	v_cvt_pk_bf16_f32 v107, v212, v213
	v_cvt_pk_bf16_f32 v108, v214, v215
	v_cvt_pk_bf16_f32 v109, v216, v217
	global_store_dwordx4 v[144:145], v[106:109], off offset:256
	v_mul_f32_e32 v211, v211, v211
	v_mul_f32_e32 v213, v213, v213
	v_mul_f32_e32 v215, v215, v215
	v_fmac_f32_e32 v211, v210, v210
	v_fmac_f32_e32 v213, v212, v212
	v_mul_f32_e32 v217, v217, v217
	v_fmac_f32_e32 v215, v214, v214
	v_fmac_f32_e32 v217, v216, v216
	v_add_f32_e32 v149, v211, v213
	v_add_f32_e32 v149, v149, v215
	v_add_f32_e32 v149, v217, v149
	v_add_f32_e32 v3, v3, v149
	global_load_dwordx4 v[210:213], v[142:143], off offset:512
	global_load_dwordx4 v[214:217], v[142:143], off offset:528
	v_lshl_add_u64 v[142:143], v[142:143], 0, s[62:63]
	v_mov_b32_e32 v148, v3
	v_lshl_add_u64 v[144:145], v[144:145], 0, s[64:65]
	s_nop 0
	v_permlane16_swap_b32_e32 v3, v148
	v_add_f32_e32 v3, v3, v148
	v_mov_b32_e32 v148, v3
	s_nop 1
	v_permlane32_swap_b32_e32 v3, v148
	v_add_f32_e32 v3, v3, v148
	s_and_saveexec_b64 s[26:27], s[4:5]
	global_store_dword v[146:147], v3, off
	s_or_b64 exec, exec, s[26:27]
	v_lshl_add_u64 v[146:147], v[146:147], 0, s[28:29]
	s_waitcnt vmcnt(18)
	v_pk_add_f32 v[220:221], v[100:101], v[220:221]
	v_pk_add_f32 v[218:219], v[98:99], v[218:219]
	v_pk_add_f32 v[224:225], v[96:97], v[224:225]
	v_pk_add_f32 v[222:223], v[94:95], v[222:223]
	v_cvt_pk_bf16_f32 v98, v218, v219
	v_cvt_pk_bf16_f32 v99, v220, v221
	v_cvt_pk_bf16_f32 v100, v222, v223
	v_cvt_pk_bf16_f32 v101, v224, v225
	global_store_dwordx4 v[144:145], v[98:101], off
	v_mul_f32_e32 v3, v219, v219
	v_mul_f32_e32 v221, v221, v221
	v_mul_f32_e32 v223, v223, v223
	v_fmac_f32_e32 v3, v218, v218
	v_fmac_f32_e32 v221, v220, v220
	v_mul_f32_e32 v225, v225, v225
	v_fmac_f32_e32 v223, v222, v222
	v_add_f32_e32 v3, v3, v221
	v_fmac_f32_e32 v225, v224, v224
	v_add_f32_e32 v3, v3, v223
	v_add_f32_e32 v3, v225, v3
	global_load_dwordx4 v[218:221], v[142:143], off
	global_load_dwordx4 v[222:225], v[142:143], off offset:16
	s_waitcnt vmcnt(19)
	v_pk_add_f32 v[228:229], v[92:93], v[228:229]
	v_pk_add_f32 v[226:227], v[90:91], v[226:227]
	v_pk_add_f32 v[232:233], v[88:89], v[232:233]
	v_pk_add_f32 v[230:231], v[86:87], v[230:231]
	v_cvt_pk_bf16_f32 v90, v226, v227
	v_cvt_pk_bf16_f32 v91, v228, v229
	v_cvt_pk_bf16_f32 v92, v230, v231
	v_cvt_pk_bf16_f32 v93, v232, v233
	global_store_dwordx4 v[144:145], v[90:93], off offset:256
	v_mul_f32_e32 v227, v227, v227
	v_mul_f32_e32 v229, v229, v229
	v_mul_f32_e32 v231, v231, v231
	v_fmac_f32_e32 v227, v226, v226
	v_fmac_f32_e32 v229, v228, v228
	v_mul_f32_e32 v233, v233, v233
	v_fmac_f32_e32 v231, v230, v230
	v_fmac_f32_e32 v233, v232, v232
	v_add_f32_e32 v149, v227, v229
	v_add_f32_e32 v149, v149, v231
	v_add_f32_e32 v149, v233, v149
	v_add_f32_e32 v3, v3, v149
	global_load_dwordx4 v[226:229], v[142:143], off offset:512
	global_load_dwordx4 v[230:233], v[142:143], off offset:528
	v_lshl_add_u64 v[142:143], v[142:143], 0, s[62:63]
	v_mov_b32_e32 v148, v3
	v_lshl_add_u64 v[144:145], v[144:145], 0, s[64:65]
	s_nop 0
	v_permlane16_swap_b32_e32 v3, v148
	v_add_f32_e32 v3, v3, v148
	v_mov_b32_e32 v148, v3
	s_nop 1
	v_permlane32_swap_b32_e32 v3, v148
	v_add_f32_e32 v3, v3, v148
	s_and_saveexec_b64 s[26:27], s[4:5]
	global_store_dword v[146:147], v3, off
	s_or_b64 exec, exec, s[26:27]
	v_lshl_add_u64 v[146:147], v[146:147], 0, s[28:29]
	s_waitcnt vmcnt(20)
	v_pk_add_f32 v[236:237], v[84:85], v[236:237]
	v_pk_add_f32 v[234:235], v[82:83], v[234:235]
	v_pk_add_f32 v[240:241], v[80:81], v[240:241]
	v_pk_add_f32 v[238:239], v[78:79], v[238:239]
	v_cvt_pk_bf16_f32 v82, v234, v235
	v_cvt_pk_bf16_f32 v83, v236, v237
	v_cvt_pk_bf16_f32 v84, v238, v239
	v_cvt_pk_bf16_f32 v85, v240, v241
	global_store_dwordx4 v[144:145], v[82:85], off
	v_mul_f32_e32 v3, v235, v235
	v_mul_f32_e32 v237, v237, v237
	v_mul_f32_e32 v239, v239, v239
	v_fmac_f32_e32 v3, v234, v234
	v_fmac_f32_e32 v237, v236, v236
	v_mul_f32_e32 v241, v241, v241
	v_fmac_f32_e32 v239, v238, v238
	v_add_f32_e32 v3, v3, v237
	v_fmac_f32_e32 v241, v240, v240
	v_add_f32_e32 v3, v3, v239
	v_add_f32_e32 v3, v241, v3
	global_load_dwordx4 v[234:237], v[142:143], off
	global_load_dwordx4 v[238:241], v[142:143], off offset:16
	s_waitcnt vmcnt(21)
	v_pk_add_f32 v[136:137], v[76:77], v[136:137]
	v_pk_add_f32 v[134:135], v[74:75], v[134:135]
	v_pk_add_f32 v[140:141], v[72:73], v[140:141]
	v_pk_add_f32 v[138:139], v[70:71], v[138:139]
	v_cvt_pk_bf16_f32 v74, v134, v135
	v_cvt_pk_bf16_f32 v75, v136, v137
	v_cvt_pk_bf16_f32 v76, v138, v139
	v_cvt_pk_bf16_f32 v77, v140, v141
	global_store_dwordx4 v[144:145], v[74:77], off offset:256
	v_mul_f32_e32 v135, v135, v135
	v_mul_f32_e32 v137, v137, v137
	v_mul_f32_e32 v139, v139, v139
	v_fmac_f32_e32 v135, v134, v134
	v_fmac_f32_e32 v137, v136, v136
	v_mul_f32_e32 v141, v141, v141
	v_fmac_f32_e32 v139, v138, v138
	v_fmac_f32_e32 v141, v140, v140
	v_add_f32_e32 v149, v135, v137
	v_add_f32_e32 v149, v149, v139
	v_add_f32_e32 v149, v141, v149
	v_add_f32_e32 v3, v3, v149
	global_load_dwordx4 v[134:137], v[142:143], off offset:512
	global_load_dwordx4 v[138:141], v[142:143], off offset:528
	v_lshl_add_u64 v[142:143], v[142:143], 0, s[62:63]
	v_mov_b32_e32 v148, v3
	v_lshl_add_u64 v[144:145], v[144:145], 0, s[64:65]
	s_nop 0
	v_permlane16_swap_b32_e32 v3, v148
	v_add_f32_e32 v3, v3, v148
	v_mov_b32_e32 v148, v3
	s_nop 1
	v_permlane32_swap_b32_e32 v3, v148
	v_add_f32_e32 v3, v3, v148
	s_and_saveexec_b64 s[26:27], s[4:5]
	global_store_dword v[146:147], v3, off
	s_or_b64 exec, exec, s[26:27]
	v_lshl_add_u64 v[146:147], v[146:147], 0, s[28:29]
	s_waitcnt vmcnt(21)
; __device__ __forceinline__ unsigned pk2(float lo, float hi) { f32x2 v = {lo, hi}; bf16x2_t b = __builtin_convertvector(v, bf16x2_t); return __builtin_bit_cast(unsigned, b); }
;     __device__ __forceinline__ void operator()(const f32x4 (&acc)[2][2][4][2], const Unit& u, int wr, int wc, int fr, int fq) const {
; #pragma unroll
;         for (int ai = 0; ai < 2; ++ai)
; #pragma unroll
;             for (int m = 0; m < 4; ++m) {
;                 const size_t row = (size_t)u.pm * 256 + 128 * wr + 64 * ai + 16 * m + fr;
;                 const size_t off = row * DM + 256 * u.pn + 32 * wc + 8 * fq;
;                 float s = 0.f;
; #pragma unroll
;                 for (int bj = 0; bj < 2; ++bj) {
;                     const f32x4 v0 = *(const f32x4*)(x + off + 128 * bj) + acc[ai][bj][m][0], v1 = *(const f32x4*)(x + off + 128 * bj + 4) + acc[ai][bj][m][1];
;                     s += (v0[0] * v0[0] + v0[1] * v0[1]) + (v0[2] * v0[2] + v0[3] * v0[3]) + (v1[0] * v1[0] + v1[1] * v1[1]) + (v1[2] * v1[2] + v1[3] * v1[3]);
;                     u32x4 w; w.x = pk2(v0[0], v0[1]); w.y = pk2(v0[2], v0[3]); w.z = pk2(v1[0], v1[1]); w.w = pk2(v1[2], v1[3]);
;                     *(u32x4*)(XB + off + 128 * bj) = w;
;                 }
;                 s = xor16_32_sum(s);
;                 if (fq == 0) ssq[row * 16 + u.pn * 4 + wc] = s;
;             }
	v_pk_add_f32 v[188:189], v[68:69], v[188:189]
	v_pk_add_f32 v[186:187], v[66:67], v[186:187]
	v_pk_add_f32 v[192:193], v[64:65], v[192:193]
	v_pk_add_f32 v[190:191], v[62:63], v[190:191]
	v_cvt_pk_bf16_f32 v66, v186, v187
	v_cvt_pk_bf16_f32 v67, v188, v189
	v_cvt_pk_bf16_f32 v68, v190, v191
	v_cvt_pk_bf16_f32 v69, v192, v193
	global_store_dwordx4 v[144:145], v[66:69], off
	v_mul_f32_e32 v3, v187, v187
	v_mul_f32_e32 v189, v189, v189
	v_mul_f32_e32 v191, v191, v191
	v_fmac_f32_e32 v3, v186, v186
	v_fmac_f32_e32 v189, v188, v188
	v_mul_f32_e32 v193, v193, v193
	v_fmac_f32_e32 v191, v190, v190
	v_add_f32_e32 v3, v3, v189
	v_fmac_f32_e32 v193, v192, v192
	v_add_f32_e32 v3, v3, v191
	v_add_f32_e32 v3, v193, v3
	s_waitcnt vmcnt(19)
	v_pk_add_f32 v[196:197], v[60:61], v[196:197]
	v_pk_add_f32 v[194:195], v[58:59], v[194:195]
	v_pk_add_f32 v[200:201], v[56:57], v[200:201]
	v_pk_add_f32 v[198:199], v[54:55], v[198:199]
	v_cvt_pk_bf16_f32 v58, v194, v195
	v_cvt_pk_bf16_f32 v59, v196, v197
	v_cvt_pk_bf16_f32 v60, v198, v199
	v_cvt_pk_bf16_f32 v61, v200, v201
	global_store_dwordx4 v[144:145], v[58:61], off offset:256
	v_mul_f32_e32 v195, v195, v195
	v_mul_f32_e32 v197, v197, v197
	v_mul_f32_e32 v199, v199, v199
	v_fmac_f32_e32 v195, v194, v194
	v_fmac_f32_e32 v197, v196, v196
	v_mul_f32_e32 v201, v201, v201
	v_fmac_f32_e32 v199, v198, v198
	v_fmac_f32_e32 v201, v200, v200
	v_add_f32_e32 v149, v195, v197
	v_add_f32_e32 v149, v149, v199
	v_add_f32_e32 v149, v201, v149
	v_add_f32_e32 v3, v3, v149
	v_mov_b32_e32 v148, v3
	v_lshl_add_u64 v[144:145], v[144:145], 0, s[64:65]
	s_nop 0
	v_permlane16_swap_b32_e32 v3, v148
	v_add_f32_e32 v3, v3, v148
	v_mov_b32_e32 v148, v3
	s_nop 1
	v_permlane32_swap_b32_e32 v3, v148
	v_add_f32_e32 v3, v3, v148
	s_and_saveexec_b64 s[26:27], s[4:5]
	global_store_dword v[146:147], v3, off
	s_or_b64 exec, exec, s[26:27]
	v_lshl_add_u64 v[146:147], v[146:147], 0, s[28:29]
	s_waitcnt vmcnt(17)
	v_pk_add_f32 v[204:205], v[52:53], v[204:205]
	v_pk_add_f32 v[202:203], v[50:51], v[202:203]
	v_pk_add_f32 v[208:209], v[48:49], v[208:209]
	v_pk_add_f32 v[206:207], v[46:47], v[206:207]
	v_cvt_pk_bf16_f32 v50, v202, v203
	v_cvt_pk_bf16_f32 v51, v204, v205
	v_cvt_pk_bf16_f32 v52, v206, v207
	v_cvt_pk_bf16_f32 v53, v208, v209
	global_store_dwordx4 v[144:145], v[50:53], off
	v_mul_f32_e32 v3, v203, v203
	v_mul_f32_e32 v205, v205, v205
	v_mul_f32_e32 v207, v207, v207
	v_fmac_f32_e32 v3, v202, v202
	v_fmac_f32_e32 v205, v204, v204
	v_mul_f32_e32 v209, v209, v209
	v_fmac_f32_e32 v207, v206, v206
	v_add_f32_e32 v3, v3, v205
	v_fmac_f32_e32 v209, v208, v208
	v_add_f32_e32 v3, v3, v207
	v_add_f32_e32 v3, v209, v3
	s_waitcnt vmcnt(15)
	v_pk_add_f32 v[212:213], v[44:45], v[212:213]
	v_pk_add_f32 v[210:211], v[42:43], v[210:211]
	v_pk_add_f32 v[216:217], v[40:41], v[216:217]
	v_pk_add_f32 v[214:215], v[38:39], v[214:215]
	v_cvt_pk_bf16_f32 v42, v210, v211
	v_cvt_pk_bf16_f32 v43, v212, v213
	v_cvt_pk_bf16_f32 v44, v214, v215
	v_cvt_pk_bf16_f32 v45, v216, v217
	global_store_dwordx4 v[144:145], v[42:45], off offset:256
	v_mul_f32_e32 v211, v211, v211
	v_mul_f32_e32 v213, v213, v213
	v_mul_f32_e32 v215, v215, v215
	v_fmac_f32_e32 v211, v210, v210
	v_fmac_f32_e32 v213, v212, v212
	v_mul_f32_e32 v217, v217, v217
	v_fmac_f32_e32 v215, v214, v214
	v_fmac_f32_e32 v217, v216, v216
	v_add_f32_e32 v149, v211, v213
	v_add_f32_e32 v149, v149, v215
	v_add_f32_e32 v149, v217, v149
	v_add_f32_e32 v3, v3, v149
	v_mov_b32_e32 v148, v3
	v_lshl_add_u64 v[144:145], v[144:145], 0, s[64:65]
	s_nop 0
	v_permlane16_swap_b32_e32 v3, v148
	v_add_f32_e32 v3, v3, v148
	v_mov_b32_e32 v148, v3
	s_nop 1
	v_permlane32_swap_b32_e32 v3, v148
	v_add_f32_e32 v3, v3, v148
	s_and_saveexec_b64 s[26:27], s[4:5]
	global_store_dword v[146:147], v3, off
	s_or_b64 exec, exec, s[26:27]
	v_lshl_add_u64 v[146:147], v[146:147], 0, s[28:29]
	s_waitcnt vmcnt(13)
; __device__ __forceinline__ unsigned pk2(float lo, float hi) { f32x2 v = {lo, hi}; bf16x2_t b = __builtin_convertvector(v, bf16x2_t); return __builtin_bit_cast(unsigned, b); }
; #define PG8_BAR __builtin_amdgcn_s_barrier()
;     __device__ __forceinline__ void operator()(const f32x4 (&acc)[2][2][4][2], const Unit& u, int wr, int wc, int fr, int fq) const {
;     ...
;                 const size_t row = (size_t)u.pm * 256 + 128 * wr + 64 * ai + 16 * m + fr;
;                 const size_t off = row * DM + 256 * u.pn + 32 * wc + 8 * fq;
;                 float s = 0.f;
; #pragma unroll
;                 for (int bj = 0; bj < 2; ++bj) {
;                     const f32x4 v0 = *(const f32x4*)(x + off + 128 * bj) + acc[ai][bj][m][0], v1 = *(const f32x4*)(x + off + 128 * bj + 4) + acc[ai][bj][m][1];
;                     s += (v0[0] * v0[0] + v0[1] * v0[1]) + (v0[2] * v0[2] + v0[3] * v0[3]) + (v1[0] * v1[0] + v1[1] * v1[1]) + (v1[2] * v1[2] + v1[3] * v1[3]);
;                     u32x4 w; w.x = pk2(v0[0], v0[1]); w.y = pk2(v0[2], v0[3]); w.z = pk2(v1[0], v1[1]); w.w = pk2(v1[2], v1[3]);
;                     *(u32x4*)(XB + off + 128 * bj) = w;
;                 }
;                 s = xor16_32_sum(s);
;                 if (fq == 0) ssq[row * 16 + u.pn * 4 + wc] = s;
;             }
; template <class Epi, class Sched>
; __device__ __forceinline__ void gemm_phase(LAS unsigned char* lds, const Gemm g, const Sched& S, const Epi& E) {
;     ...
;         if (!has_next) break;
; #pragma unroll
;         for (int a = 0; a < 2; ++a)
; #pragma unroll
;             for (int b = 0; b < 2; ++b)
; #pragma unroll
;                 for (int m = 0; m < 4; ++m)
; #pragma unroll
;                     for (int n = 0; n < 2; ++n) acc[a][b][m][n] = (f32x4){0.f, 0.f, 0.f, 0.f};
;         cur = nxt; cA = nA; cB = nB; ++ui;
;         if (wr == 1) PG8_BAR;
	v_pk_add_f32 v[220:221], v[36:37], v[220:221]
	v_pk_add_f32 v[218:219], v[34:35], v[218:219]
	v_pk_add_f32 v[224:225], v[32:33], v[224:225]
	v_pk_add_f32 v[222:223], v[30:31], v[222:223]
	v_cvt_pk_bf16_f32 v34, v218, v219
	v_cvt_pk_bf16_f32 v35, v220, v221
	v_cvt_pk_bf16_f32 v36, v222, v223
	v_cvt_pk_bf16_f32 v37, v224, v225
	global_store_dwordx4 v[144:145], v[34:37], off
	v_mul_f32_e32 v3, v219, v219
	v_mul_f32_e32 v221, v221, v221
	v_mul_f32_e32 v223, v223, v223
	v_fmac_f32_e32 v3, v218, v218
	v_fmac_f32_e32 v221, v220, v220
	v_mul_f32_e32 v225, v225, v225
	v_fmac_f32_e32 v223, v222, v222
	v_add_f32_e32 v3, v3, v221
	v_fmac_f32_e32 v225, v224, v224
	v_add_f32_e32 v3, v3, v223
	v_add_f32_e32 v3, v225, v3
	s_waitcnt vmcnt(11)
	v_pk_add_f32 v[228:229], v[28:29], v[228:229]
	v_pk_add_f32 v[226:227], v[26:27], v[226:227]
	v_pk_add_f32 v[232:233], v[24:25], v[232:233]
	v_pk_add_f32 v[230:231], v[22:23], v[230:231]
	v_cvt_pk_bf16_f32 v26, v226, v227
	v_cvt_pk_bf16_f32 v27, v228, v229
	v_cvt_pk_bf16_f32 v28, v230, v231
	v_cvt_pk_bf16_f32 v29, v232, v233
	global_store_dwordx4 v[144:145], v[26:29], off offset:256
	v_mul_f32_e32 v227, v227, v227
	v_mul_f32_e32 v229, v229, v229
	v_mul_f32_e32 v231, v231, v231
	v_fmac_f32_e32 v227, v226, v226
	v_fmac_f32_e32 v229, v228, v228
	v_mul_f32_e32 v233, v233, v233
	v_fmac_f32_e32 v231, v230, v230
	v_fmac_f32_e32 v233, v232, v232
	v_add_f32_e32 v149, v227, v229
	v_add_f32_e32 v149, v149, v231
	v_add_f32_e32 v149, v233, v149
	v_add_f32_e32 v3, v3, v149
	v_mov_b32_e32 v148, v3
	v_lshl_add_u64 v[144:145], v[144:145], 0, s[64:65]
	s_nop 0
	v_permlane16_swap_b32_e32 v3, v148
	v_add_f32_e32 v3, v3, v148
	v_mov_b32_e32 v148, v3
	s_nop 1
	v_permlane32_swap_b32_e32 v3, v148
	v_add_f32_e32 v3, v3, v148
	s_and_saveexec_b64 s[26:27], s[4:5]
	global_store_dword v[146:147], v3, off
	s_or_b64 exec, exec, s[26:27]
	v_lshl_add_u64 v[146:147], v[146:147], 0, s[28:29]
	s_waitcnt vmcnt(9)
	v_pk_add_f32 v[236:237], v[20:21], v[236:237]
	v_pk_add_f32 v[234:235], v[18:19], v[234:235]
	v_pk_add_f32 v[240:241], v[16:17], v[240:241]
	v_pk_add_f32 v[238:239], v[14:15], v[238:239]
	v_cvt_pk_bf16_f32 v18, v234, v235
	v_cvt_pk_bf16_f32 v19, v236, v237
	v_cvt_pk_bf16_f32 v20, v238, v239
	v_cvt_pk_bf16_f32 v21, v240, v241
	global_store_dwordx4 v[144:145], v[18:21], off
	v_mul_f32_e32 v3, v235, v235
	v_mul_f32_e32 v237, v237, v237
	v_mul_f32_e32 v239, v239, v239
	v_fmac_f32_e32 v3, v234, v234
	v_fmac_f32_e32 v237, v236, v236
	v_mul_f32_e32 v241, v241, v241
	v_fmac_f32_e32 v239, v238, v238
	v_add_f32_e32 v3, v3, v237
	v_fmac_f32_e32 v241, v240, v240
	v_add_f32_e32 v3, v3, v239
	v_add_f32_e32 v3, v241, v3
	s_waitcnt vmcnt(7)
	v_pk_add_f32 v[136:137], v[12:13], v[136:137]
	v_pk_add_f32 v[134:135], v[10:11], v[134:135]
	v_pk_add_f32 v[140:141], v[8:9], v[140:141]
	v_pk_add_f32 v[138:139], v[6:7], v[138:139]
	v_cvt_pk_bf16_f32 v10, v134, v135
	v_cvt_pk_bf16_f32 v11, v136, v137
	v_cvt_pk_bf16_f32 v12, v138, v139
	v_cvt_pk_bf16_f32 v13, v140, v141
	global_store_dwordx4 v[144:145], v[10:13], off offset:256
	v_mul_f32_e32 v135, v135, v135
	v_mul_f32_e32 v137, v137, v137
	v_mul_f32_e32 v139, v139, v139
	v_fmac_f32_e32 v135, v134, v134
	v_fmac_f32_e32 v137, v136, v136
	v_mul_f32_e32 v141, v141, v141
	v_fmac_f32_e32 v139, v138, v138
	v_fmac_f32_e32 v141, v140, v140
	v_add_f32_e32 v149, v135, v137
	v_add_f32_e32 v149, v149, v139
	v_add_f32_e32 v149, v141, v149
	v_add_f32_e32 v3, v3, v149
	v_mov_b32_e32 v148, v3
	s_nop 0
	s_nop 0
	v_permlane16_swap_b32_e32 v3, v148
	v_add_f32_e32 v3, v3, v148
	v_mov_b32_e32 v148, v3
	s_nop 1
	v_permlane32_swap_b32_e32 v3, v148
	v_add_f32_e32 v3, v3, v148
	s_and_saveexec_b64 s[26:27], s[4:5]
	global_store_dword v[146:147], v3, off
	s_or_b64 exec, exec, s[26:27]
	s_andn2_b64 vcc, exec, s[6:7]
	s_mov_b64 s[6:7], -1
	s_cbranch_vccnz .LBB0_608
	s_andn2_b64 vcc, exec, s[8:9]
	s_cbranch_vccnz .LBB0_607
	s_barrier
	s_branch .LBB0_607
